# in-proj GEMM K-loop: scalar-base (SALU-advanced) + loop-invariant 32-bit VGPR offsets for global loads instead of 64-bit VALU address math; on top of attention copy removal and restructured GEMM loops
# speedup vs baseline: 1.0324x; 1.0065x over previous
; DI int otid() { int t = threadIdx.x; asm volatile("" : "+v"(t)); return t; }
; DI f32x16 fzero() { f32x16 z; for (int i = 0; i < 16; ++i) z[i] = 0.f; return z; }
; template <int TJ>
; DI void gemm_core(const u16* __restrict__ W, int ldw, const u16* __restrict__ X, int ldx, int K, f32x16 (&acc)[2][TJ], char* lds) {
;     ...
;   const int tid = otid(), lane = tid & 63, wid = tid >> 6, r = lane & 31, h = lane >> 5;
;   const int wn = wid & 1, wt = wid >> 1;
;   u32x4 wA[2], xA[TJ], wB[2], xB[TJ];
;   const int lrow = tid >> 2, lch = tid & 3;
;   const u16* wp = W + (size_t)lrow * ldw + lch * 8;
;   const u16* xp = X + (size_t)lrow * ldx + lch * 8;
;   const int nk = K / 32;
;     ...
;   G_LOAD(wA, xA, 0);
;   G_LOAD(wB, xB, 1);
;   G_STORE(wA, xA, 0);
; DI void phase_inproj(const Params& p, int layer, char* lds) {
;     ...
;   const int xcd = blockIdx.x & 7, li = blockIdx.x >> 3, nloc = gridDim.x >> 3;
;   for (int q = li; q < 6 * 17 * 8; q += nloc) {
;     const int ni = q & 7, a = (q >> 3) % 17, ng = (q >> 3) / 17;
;     const int tt = 8 * a + xcd, nt = ng * 8 + ni;
;     if (nt >= 47) continue;
;     f32x16 acc[2][4];
; #pragma unroll
;     for (int i = 0; i < 2; ++i)
; #pragma unroll
;       for (int j = 0; j < 4; ++j) acc[i][j] = fzero();
;     gemm_core<4>(Wt + (size_t)nt * 128 * 1024, 1024, H + (size_t)tt * 256 * 1024, 1024, 1024, acc, lds);
.LBB0_422:
	s_mul_i32 s1, s45, 0xf0f1
	s_lshr_b32 s1, s1, 20
	s_and_b32 s0, s45, 7
	s_and_b32 s1, s1, 0xff8
	s_or_b32 s36, s0, s1
	s_cmp_gt_u32 s36, 46
	s_cbranch_scc1 .LBB0_421
	s_bfe_u32 s0, s45, 0x80003
	s_mulk_i32 s0, 0xf1
	s_lshr_b32 s30, s0, 12
	s_lshr_b32 s26, s45, 3
	s_mul_i32 s0, s30, 0x78
	s_and_b32 s1, s45, -8
	s_mul_i32 s30, s30, 17
	s_add_i32 s0, s0, s1
	s_and_b32 s1, 0xffff, s44
	s_sub_i32 s26, s26, s30
	s_and_b32 s0, s0, 0xf8
	v_readlane_b32 s37, v252, 23
	s_mul_hi_u32 s1, s1, 0x1e1e1e2
	s_and_b32 s31, s35, 7
	s_lshl_b32 s26, s26, 3
	s_or_b32 s0, s37, s0
	s_lshl_b32 s31, s31, 18
	s_lshl_b32 s1, s1, 21
	s_and_b32 s26, s26, 0xf8
	v_mov_b32_e32 v16, v190
	s_lshl_b32 s0, s0, 19
	s_or_b32 s1, s1, s31
	s_or_b32 s38, s37, s26
	s_lshl_b32 s26, s36, 18
	v_readlane_b32 s30, v252, 21
	v_readlane_b32 s31, v252, 22
	v_ashrrev_i32_e32 v0, 2, v16
	s_add_u32 s30, s30, s26
	v_ashrrev_i32_e32 v1, 31, v0
	s_addc_u32 s31, s31, 0
	s_lshl_b32 s26, s38, 8
	s_lshl_b32 s37, s38, 19
	v_readlane_b32 s40, v252, 26
	v_and_b32_e32 v17, 3, v16
	v_lshlrev_b64 v[2:3], 11, v[0:1]
	v_readlane_b32 s41, v252, 27
	s_add_u32 s40, s40, s37
	v_lshl_add_u64 v[4:5], s[30:31], 0, v[2:3]
	v_lshlrev_b32_e32 v64, 4, v17
	s_addc_u32 s41, s41, 0
	s_mov_b64 s[56:57], s[30:31]
	s_mov_b64 s[54:55], s[40:41]
	v_add_u32_e32 v186, v2, v64
	v_add_u32_e32 v187, 0x20000, v186
	v_add_u32_e32 v188, 0x40000, v186
	v_add_u32_e32 v189, 0x60000, v186
	v_lshl_add_u64 v[4:5], v[4:5], 0, v[64:65]
	s_mov_b32 s18, 0x20000
	v_lshl_add_u64 v[6:7], s[40:41], 0, v[2:3]
	v_add_co_u32_e32 v8, vcc, s18, v4
	v_lshl_add_u64 v[6:7], v[6:7], 0, v[64:65]
	s_nop 0
	v_addc_co_u32_e32 v9, vcc, 0, v5, vcc
	v_add_co_u32_e32 v10, vcc, s18, v6
	s_mov_b32 s30, 0x40000
	s_nop 0
	v_addc_co_u32_e32 v11, vcc, 0, v7, vcc
	v_add_co_u32_e32 v12, vcc, s30, v6
	s_mov_b32 s30, 0x60000
	s_nop 0
	v_addc_co_u32_e32 v13, vcc, 0, v7, vcc
	v_add_co_u32_e32 v14, vcc, s30, v6
	global_load_dwordx4 v[130:133], v[4:5], off
	global_load_dwordx4 v[138:141], v[6:7], off
	v_addc_co_u32_e32 v15, vcc, 0, v7, vcc
	global_load_dwordx4 v[134:137], v[8:9], off
	global_load_dwordx4 v[142:145], v[10:11], off
	global_load_dwordx4 v[154:157], v[12:13], off
	global_load_dwordx4 v[162:165], v[14:15], off
	global_load_dwordx4 v[146:149], v[4:5], off offset:64
	global_load_dwordx4 v[150:153], v[8:9], off offset:64
	global_load_dwordx4 v[158:161], v[6:7], off offset:64
	global_load_dwordx4 v[166:169], v[10:11], off offset:64
	global_load_dwordx4 v[170:173], v[12:13], off offset:64
	global_load_dwordx4 v[174:177], v[14:15], off offset:64
	v_lshlrev_b32_e32 v18, 11, v17
	v_lshlrev_b32_e32 v17, 5, v17
	v_lshlrev_b32_e32 v0, 4, v0
	v_bfe_u32 v1, v16, 5, 1
	v_xor_b32_e32 v21, v0, v17
	v_add_u32_e32 v22, 0x400, v0
	v_add_u32_e32 v24, 0x800, v0
	v_add_u32_e32 v0, 0xc00, v0
	v_lshlrev_b32_e32 v19, 11, v1
	v_lshlrev_b32_e32 v20, 5, v1
	v_add_u32_e32 v23, v18, v18
	v_xor_b32_e32 v0, v0, v17
	v_or_b32_e32 v1, 2, v1
	v_add_u32_e32 v219, v23, v0
	v_lshlrev_b32_e32 v0, 4, v16
	s_movk_i32 s30, 0x5f0
	v_lshlrev_b32_e32 v13, 11, v1
	v_lshlrev_b32_e32 v1, 5, v1
	v_bitop3_b32 v5, v20, v0, s30 bitop3:0x78
	s_movk_i32 s31, 0xf9f0
	v_bitop3_b32 v14, v1, v0, s30 bitop3:0x78
	s_add_u32 s30, s22, s0
	v_bitop3_b32 v9, v20, v0, s31 bitop3:0x78
	v_bitop3_b32 v16, v1, v0, s31 bitop3:0x78
	s_addc_u32 s31, s23, 0
	v_and_b32_e32 v4, 0x5f0, v0
	s_movk_i32 s18, 0x200
	v_and_b32_e32 v8, 0xfffff9f0, v0
	s_movk_i32 s19, 0x400
	s_movk_i32 s37, 0x600
	s_add_u32 s0, s22, s1
	v_add_u32_e32 v214, v18, v21
	v_xor_b32_e32 v22, v22, v17
	v_add_u32_e32 v215, v23, v21
	v_xor_b32_e32 v21, v24, v17
	v_bitop3_b32 v6, v4, v20, s18 bitop3:0x36
	v_add_u32_e32 v7, v19, v19
	v_bitop3_b32 v10, v8, v20, s18 bitop3:0x36
	v_bitop3_b32 v11, v8, v20, s19 bitop3:0x36
	v_bitop3_b32 v12, v20, v0, s37 bitop3:0x1e
	v_bitop3_b32 v4, v1, v4, s18 bitop3:0x1e
	v_add_u32_e32 v15, v13, v13
	v_bitop3_b32 v17, v1, v8, s18 bitop3:0x1e
	v_bitop3_b32 v8, v1, v8, s19 bitop3:0x1e
	v_bitop3_b32 v1, v1, v0, s37 bitop3:0x1e
	s_addc_u32 s1, s23, 0
	v_mov_b32_e32 v0, 0
	v_add_u32_e32 v216, v18, v22
	v_add_u32_e32 v217, v23, v22
	v_add_u32_e32 v218, v23, v21
	v_lshl_add_u64 v[182:183], s[30:31], 0, v[2:3]
	v_lshl_add_u64 v[184:185], s[0:1], 0, v[2:3]
	s_mov_b32 s37, -2
	v_add_u32_e32 v220, v19, v5
	v_add_u32_e32 v221, v19, v6
	v_add_u32_e32 v222, v7, v9
	v_add_u32_e32 v223, v7, v10
	v_add_u32_e32 v224, v7, v11
	v_add_u32_e32 v225, v7, v12
	v_add_u32_e32 v226, v13, v14
	v_add_u32_e32 v227, v13, v4
	v_add_u32_e32 v228, v15, v16
	v_add_u32_e32 v229, v15, v17
	v_add_u32_e32 v230, v15, v8
	v_add_u32_e32 v231, v15, v1
	v_mov_b32_e32 v1, v0
	v_mov_b32_e32 v2, v0
	v_mov_b32_e32 v3, v0
	v_mov_b32_e32 v4, v0
	v_mov_b32_e32 v5, v0
	v_mov_b32_e32 v6, v0
	v_mov_b32_e32 v7, v0
	v_mov_b32_e32 v8, v0
	v_mov_b32_e32 v9, v0
	v_mov_b32_e32 v10, v0
	v_mov_b32_e32 v11, v0
	v_mov_b32_e32 v12, v0
	v_mov_b32_e32 v13, v0
	v_mov_b32_e32 v14, v0
	v_mov_b32_e32 v15, v0
	v_mov_b32_e32 v32, v0
	v_mov_b32_e32 v33, v0
	v_mov_b32_e32 v34, v0
	v_mov_b32_e32 v35, v0
	v_mov_b32_e32 v36, v0
	v_mov_b32_e32 v37, v0
	v_mov_b32_e32 v38, v0
	v_mov_b32_e32 v39, v0
	v_mov_b32_e32 v40, v0
	v_mov_b32_e32 v41, v0
	v_mov_b32_e32 v42, v0
	v_mov_b32_e32 v43, v0
	v_mov_b32_e32 v44, v0
	v_mov_b32_e32 v45, v0
	v_mov_b32_e32 v46, v0
	v_mov_b32_e32 v47, v0
	v_mov_b32_e32 v66, v0
	v_mov_b32_e32 v67, v0
	v_mov_b32_e32 v68, v0
	v_mov_b32_e32 v69, v0
	v_mov_b32_e32 v70, v0
	v_mov_b32_e32 v71, v0
	v_mov_b32_e32 v72, v0
	v_mov_b32_e32 v73, v0
	v_mov_b32_e32 v74, v0
	v_mov_b32_e32 v75, v0
	v_mov_b32_e32 v76, v0
	v_mov_b32_e32 v77, v0
	v_mov_b32_e32 v78, v0
	v_mov_b32_e32 v79, v0
; template <int TJ>
; DI void gemm_core(const u16* __restrict__ W, int ldw, const u16* __restrict__ X, int ldx, int K, f32x16 (&acc)[2][TJ], char* lds) {
;     ...
;   G_LOAD(wA, xA, 0);
;   G_LOAD(wB, xB, 1);
;   G_STORE(wA, xA, 0);
;   __syncthreads();
;   for (int kt = 0; kt < nk; kt += 2) {
;     if (kt + 2 < nk) G_LOAD(wA, xA, kt + 2);
;     G_COMPUTE(0);
;     G_STORE(wB, xB, 1);
;     __syncthreads();
;     if (kt + 3 < nk) G_LOAD(wB, xB, kt + 3);
;     G_COMPUTE(1);
;     if (kt + 2 < nk) G_STORE(wA, xA, 0);
;     __syncthreads();
;   }
	v_mov_b32_e32 v80, v0
	v_mov_b32_e32 v81, v0
	v_mov_b32_e32 v98, v0
	v_mov_b32_e32 v99, v0
	v_mov_b32_e32 v100, v0
	v_mov_b32_e32 v101, v0
	v_mov_b32_e32 v102, v0
	v_mov_b32_e32 v103, v0
	v_mov_b32_e32 v104, v0
	v_mov_b32_e32 v105, v0
	v_mov_b32_e32 v106, v0
	v_mov_b32_e32 v107, v0
	v_mov_b32_e32 v108, v0
	v_mov_b32_e32 v109, v0
	v_mov_b32_e32 v110, v0
	v_mov_b32_e32 v111, v0
	v_mov_b32_e32 v112, v0
	v_mov_b32_e32 v113, v0
	v_mov_b32_e32 v16, v0
	v_mov_b32_e32 v17, v0
	v_mov_b32_e32 v18, v0
	v_mov_b32_e32 v19, v0
	v_mov_b32_e32 v20, v0
	v_mov_b32_e32 v21, v0
	v_mov_b32_e32 v22, v0
	v_mov_b32_e32 v23, v0
	v_mov_b32_e32 v24, v0
	v_mov_b32_e32 v25, v0
	v_mov_b32_e32 v26, v0
	v_mov_b32_e32 v27, v0
	v_mov_b32_e32 v28, v0
	v_mov_b32_e32 v29, v0
	v_mov_b32_e32 v30, v0
	v_mov_b32_e32 v31, v0
	v_mov_b32_e32 v48, v0
	v_mov_b32_e32 v49, v0
	v_mov_b32_e32 v50, v0
	v_mov_b32_e32 v51, v0
	v_mov_b32_e32 v52, v0
	v_mov_b32_e32 v53, v0
	v_mov_b32_e32 v54, v0
	v_mov_b32_e32 v55, v0
	v_mov_b32_e32 v56, v0
	v_mov_b32_e32 v57, v0
	v_mov_b32_e32 v58, v0
	v_mov_b32_e32 v59, v0
	v_mov_b32_e32 v60, v0
	v_mov_b32_e32 v61, v0
	v_mov_b32_e32 v62, v0
	v_mov_b32_e32 v63, v0
	v_mov_b32_e32 v82, v0
	v_mov_b32_e32 v83, v0
	v_mov_b32_e32 v84, v0
	v_mov_b32_e32 v85, v0
	v_mov_b32_e32 v86, v0
	v_mov_b32_e32 v87, v0
	v_mov_b32_e32 v88, v0
	v_mov_b32_e32 v89, v0
	v_mov_b32_e32 v90, v0
	v_mov_b32_e32 v91, v0
	v_mov_b32_e32 v92, v0
	v_mov_b32_e32 v93, v0
	v_mov_b32_e32 v94, v0
	v_mov_b32_e32 v95, v0
	v_mov_b32_e32 v96, v0
	v_mov_b32_e32 v97, v0
	v_mov_b32_e32 v114, v0
	v_mov_b32_e32 v115, v0
	v_mov_b32_e32 v116, v0
	v_mov_b32_e32 v117, v0
	v_mov_b32_e32 v118, v0
	v_mov_b32_e32 v119, v0
	v_mov_b32_e32 v120, v0
	v_mov_b32_e32 v121, v0
	v_mov_b32_e32 v122, v0
	v_mov_b32_e32 v123, v0
	v_mov_b32_e32 v124, v0
	v_mov_b32_e32 v125, v0
	v_mov_b32_e32 v126, v0
	v_mov_b32_e32 v127, v0
	v_mov_b32_e32 v128, v0
	v_mov_b32_e32 v129, v0
	s_waitcnt vmcnt(11)
	ds_write_b128 v214, v[130:133]
	s_waitcnt vmcnt(9)
	ds_write_b128 v216, v[134:137]
	ds_write_b128 v215, v[138:141] offset:8192
	s_waitcnt vmcnt(8)
	ds_write_b128 v217, v[142:145] offset:8192
	s_waitcnt vmcnt(7)
	ds_write_b128 v218, v[154:157] offset:8192
	s_waitcnt vmcnt(6)
	ds_write_b128 v219, v[162:165] offset:8192
	s_waitcnt lgkmcnt(0)
	s_barrier
	s_branch .LBB0_425
.LBB0_424:
	s_add_u32 s54, s54, 0x80
	s_addc_u32 s55, s55, 0
	s_add_u32 s56, s56, 0x80
	s_addc_u32 s57, s57, 0
	s_andn2_b64 vcc, exec, s[0:1]
	s_waitcnt lgkmcnt(0)
	s_barrier
	s_cbranch_vccz .LBB0_431
.LBB0_425:
	s_add_i32 s37, s37, 2
	s_cmp_lt_u32 s37, 30
	s_cselect_b64 s[30:31], -1, 0
	s_cmp_gt_u32 s37, 29
	s_cselect_b64 s[0:1], -1, 0
	ds_read_b128 v[232:235], v220
	ds_read_b128 v[236:239], v221
	ds_read_b128 v[240:243], v222 offset:8192
	ds_read_b128 v[244:247], v223 offset:8192
	ds_read_b128 v[248:251], v224 offset:8192
	ds_read_b128 v[206:209], v225 offset:8192
	ds_read_b128 v[130:133], v226
	ds_read_b128 v[134:137], v227
	ds_read_b128 v[138:141], v228 offset:8192
	ds_read_b128 v[142:145], v229 offset:8192
	ds_read_b128 v[154:157], v230 offset:8192
	ds_read_b128 v[162:165], v231 offset:8192
	s_setprio 1
	s_waitcnt lgkmcnt(9)
	v_mfma_f32_32x32x16_bf16 v[114:129], v[232:235], v[240:243], v[114:129]
	s_waitcnt lgkmcnt(8)
	v_mfma_f32_32x32x16_bf16 v[82:97], v[232:235], v[244:247], v[82:97]
	s_waitcnt lgkmcnt(7)
	v_mfma_f32_32x32x16_bf16 v[48:63], v[232:235], v[248:251], v[48:63]
	s_waitcnt lgkmcnt(6)
	v_mfma_f32_32x32x16_bf16 v[16:31], v[232:235], v[206:209], v[16:31]
	v_mfma_f32_32x32x16_bf16 v[98:113], v[236:239], v[240:243], v[98:113]
	v_mfma_f32_32x32x16_bf16 v[66:81], v[236:239], v[244:247], v[66:81]
	v_mfma_f32_32x32x16_bf16 v[32:47], v[236:239], v[248:251], v[32:47]
	v_mfma_f32_32x32x16_bf16 v[0:15], v[236:239], v[206:209], v[0:15]
	s_setprio 0
	s_waitcnt vmcnt(0)
	ds_write_b128 v214, v[146:149] offset:24576
	ds_write_b128 v216, v[150:153] offset:24576
	ds_write_b128 v215, v[158:161] offset:32768
	ds_write_b128 v217, v[166:169] offset:32768
	ds_write_b128 v218, v[170:173] offset:32768
	ds_write_b128 v219, v[174:177] offset:32768
	s_and_b64 vcc, exec, s[0:1]
	s_cbranch_vccnz .Lgl_ip_skipA
	s_nop 1
	global_load_dwordx4 v[146:149], v186, s[56:57] offset:128
	global_load_dwordx4 v[150:153], v187, s[56:57] offset:128
	global_load_dwordx4 v[158:161], v186, s[54:55] offset:128
	global_load_dwordx4 v[166:169], v187, s[54:55] offset:128
	global_load_dwordx4 v[170:173], v188, s[54:55] offset:128
	global_load_dwordx4 v[174:177], v189, s[54:55] offset:128
; template <int TJ>
; DI void gemm_core(const u16* __restrict__ W, int ldw, const u16* __restrict__ X, int ldx, int K, f32x16 (&acc)[2][TJ], char* lds) {
;     ...
;   G_LOAD(wA, xA, 0);
;   G_LOAD(wB, xB, 1);
;   G_STORE(wA, xA, 0);
;   __syncthreads();
;   for (int kt = 0; kt < nk; kt += 2) {
;     if (kt + 2 < nk) G_LOAD(wA, xA, kt + 2);
;     G_COMPUTE(0);
;     G_STORE(wB, xB, 1);
;     __syncthreads();
;     if (kt + 3 < nk) G_LOAD(wB, xB, kt + 3);
;     G_COMPUTE(1);
;     if (kt + 2 < nk) G_STORE(wA, xA, 0);
;     __syncthreads();
;   }
.Lgl_ip_skipA:
	s_waitcnt lgkmcnt(6)
	s_setprio 1
	v_mfma_f32_32x32x16_bf16 v[114:129], v[130:133], v[138:141], v[114:129]
	v_mfma_f32_32x32x16_bf16 v[82:97], v[130:133], v[142:145], v[82:97]
	v_mfma_f32_32x32x16_bf16 v[48:63], v[130:133], v[154:157], v[48:63]
	v_mfma_f32_32x32x16_bf16 v[16:31], v[130:133], v[162:165], v[16:31]
	v_mfma_f32_32x32x16_bf16 v[98:113], v[134:137], v[138:141], v[98:113]
	v_mfma_f32_32x32x16_bf16 v[66:81], v[134:137], v[142:145], v[66:81]
	v_mfma_f32_32x32x16_bf16 v[32:47], v[134:137], v[154:157], v[32:47]
	v_mfma_f32_32x32x16_bf16 v[0:15], v[134:137], v[162:165], v[0:15]
	s_setprio 0
	s_waitcnt lgkmcnt(0)
	s_barrier
	ds_read_b128 v[232:235], v220 offset:24576
	ds_read_b128 v[236:239], v221 offset:24576
	ds_read_b128 v[240:243], v222 offset:32768
	ds_read_b128 v[244:247], v223 offset:32768
	ds_read_b128 v[248:251], v224 offset:32768
	ds_read_b128 v[206:209], v225 offset:32768
	ds_read_b128 v[130:133], v226 offset:24576
	ds_read_b128 v[134:137], v227 offset:24576
	ds_read_b128 v[138:141], v228 offset:32768
	ds_read_b128 v[142:145], v229 offset:32768
	ds_read_b128 v[154:157], v230 offset:32768
	ds_read_b128 v[162:165], v231 offset:32768
	s_setprio 1
	s_waitcnt lgkmcnt(9)
	v_mfma_f32_32x32x16_bf16 v[114:129], v[232:235], v[240:243], v[114:129]
	s_waitcnt lgkmcnt(8)
	v_mfma_f32_32x32x16_bf16 v[82:97], v[232:235], v[244:247], v[82:97]
	s_waitcnt lgkmcnt(7)
	v_mfma_f32_32x32x16_bf16 v[48:63], v[232:235], v[248:251], v[48:63]
	s_waitcnt lgkmcnt(6)
	v_mfma_f32_32x32x16_bf16 v[16:31], v[232:235], v[206:209], v[16:31]
	v_mfma_f32_32x32x16_bf16 v[98:113], v[236:239], v[240:243], v[98:113]
	v_mfma_f32_32x32x16_bf16 v[66:81], v[236:239], v[244:247], v[66:81]
	v_mfma_f32_32x32x16_bf16 v[32:47], v[236:239], v[248:251], v[32:47]
	v_mfma_f32_32x32x16_bf16 v[0:15], v[236:239], v[206:209], v[0:15]
	s_setprio 0
	s_and_b64 vcc, exec, s[0:1]
	s_cbranch_vccnz .Lgl_ip_lastB
	s_waitcnt vmcnt(0)
	ds_write_b128 v214, v[146:149]
	ds_write_b128 v216, v[150:153]
	ds_write_b128 v215, v[158:161] offset:8192
	ds_write_b128 v217, v[166:169] offset:8192
	ds_write_b128 v218, v[170:173] offset:8192
	ds_write_b128 v219, v[174:177] offset:8192
	s_nop 1
	global_load_dwordx4 v[146:149], v186, s[56:57] offset:192
	global_load_dwordx4 v[150:153], v187, s[56:57] offset:192
	global_load_dwordx4 v[158:161], v186, s[54:55] offset:192
	global_load_dwordx4 v[166:169], v187, s[54:55] offset:192
	global_load_dwordx4 v[170:173], v188, s[54:55] offset:192
	global_load_dwordx4 v[174:177], v189, s[54:55] offset:192
	s_waitcnt lgkmcnt(6)
	s_branch .Lgl_ip_m2
